# passCml: SSD pass C decay-mask tile built with up-front cumsum reads, branch-free lane-mask select and scalar skip of empty column groups
# speedup vs baseline: 1.0064x; 1.0062x over previous
.LBB0_651:
	s_lshl_b32 s0, s96, 9
	v_lshl_add_u32 v32, v67, 2, s0
	v_lshl_add_u32 v33, v94, 2, s0
	ds_read_b128 v[36:39], v33 offset:4096
	ds_read_b32 v40, v32 offset:4096
	ds_read_b32 v41, v32 offset:4160
	ds_read_b32 v42, v32 offset:4224
	ds_read_b32 v43, v32 offset:4288
	ds_read_b32 v44, v32 offset:4352
	ds_read_b32 v45, v32 offset:4416
	ds_read_b32 v46, v32 offset:4480
	ds_read_b32 v47, v32 offset:4544
	v_mov_b32_e32 v35, 0
	s_waitcnt lgkmcnt(0)
	s_cmp_eq_u64 s[8:9], 0
	s_cbranch_scc1 .Lml_zero_0
	v_sub_f32_e32 v32, v36, v40
	v_sub_f32_e32 v33, v37, v40
	v_sub_f32_e32 v34, v38, v40
	v_sub_f32_e32 v48, v39, v40
	v_mul_f32_e32 v32, 0x3fb8aa3b, v32
	v_mul_f32_e32 v33, 0x3fb8aa3b, v33
	v_mul_f32_e32 v34, 0x3fb8aa3b, v34
	v_mul_f32_e32 v48, 0x3fb8aa3b, v48
	v_exp_f32_e32 v32, v32
	v_exp_f32_e32 v33, v33
	v_exp_f32_e32 v34, v34
	v_exp_f32_e32 v48, v48
	v_mul_f32_e32 v32, v0, v32
	v_mul_f32_e32 v33, v1, v33
	v_mul_f32_e32 v34, v2, v34
	v_mul_f32_e32 v48, v3, v48
	v_cndmask_b32_e64 v32, 0, v32, s[2:3]
	v_cndmask_b32_e64 v33, 0, v33, s[4:5]
	v_cndmask_b32_e64 v34, 0, v34, s[6:7]
	v_cndmask_b32_e64 v48, 0, v48, s[8:9]
	v_cvt_pk_bf16_f32 v32, v32, v32
	v_cvt_pk_bf16_f32 v33, v33, v33
	v_cvt_pk_bf16_f32 v34, v34, v34
	v_cvt_pk_bf16_f32 v48, v48, v48
	ds_write_b16 v119, v32 offset:43008
	ds_write_b16 v119, v33 offset:43280
	ds_write_b16 v119, v34 offset:43552
	ds_write_b16 v119, v48 offset:43824
	s_branch .Lml_next_0
.Lml_zero_0:
	ds_write_b16 v119, v35 offset:43008
	ds_write_b16 v119, v35 offset:43280
	ds_write_b16 v119, v35 offset:43552
	ds_write_b16 v119, v35 offset:43824
.Lml_next_0:
	s_cmp_eq_u64 s[16:17], 0
	s_cbranch_scc1 .Lml_zero_1
	v_sub_f32_e32 v32, v36, v41
	v_sub_f32_e32 v33, v37, v41
	v_sub_f32_e32 v34, v38, v41
	v_sub_f32_e32 v48, v39, v41
	v_mul_f32_e32 v32, 0x3fb8aa3b, v32
	v_mul_f32_e32 v33, 0x3fb8aa3b, v33
	v_mul_f32_e32 v34, 0x3fb8aa3b, v34
	v_mul_f32_e32 v48, 0x3fb8aa3b, v48
	v_exp_f32_e32 v32, v32
	v_exp_f32_e32 v33, v33
	v_exp_f32_e32 v34, v34
	v_exp_f32_e32 v48, v48
	v_mul_f32_e32 v32, v4, v32
	v_mul_f32_e32 v33, v5, v33
	v_mul_f32_e32 v34, v6, v34
	v_mul_f32_e32 v48, v7, v48
	v_cndmask_b32_e64 v32, 0, v32, s[10:11]
	v_cndmask_b32_e64 v33, 0, v33, s[12:13]
	v_cndmask_b32_e64 v34, 0, v34, s[14:15]
	v_cndmask_b32_e64 v48, 0, v48, s[16:17]
	v_cvt_pk_bf16_f32 v32, v32, v32
	v_cvt_pk_bf16_f32 v33, v33, v33
	v_cvt_pk_bf16_f32 v34, v34, v34
	v_cvt_pk_bf16_f32 v48, v48, v48
	ds_write_b16 v119, v32 offset:43040
	ds_write_b16 v119, v33 offset:43312
	ds_write_b16 v119, v34 offset:43584
	ds_write_b16 v119, v48 offset:43856
	s_branch .Lml_next_1
.Lml_zero_1:
	ds_write_b16 v119, v35 offset:43040
	ds_write_b16 v119, v35 offset:43312
	ds_write_b16 v119, v35 offset:43584
	ds_write_b16 v119, v35 offset:43856
.Lml_next_1:
	s_cmp_eq_u64 s[24:25], 0
	s_cbranch_scc1 .Lml_zero_2
	v_sub_f32_e32 v32, v36, v42
	v_sub_f32_e32 v33, v37, v42
	v_sub_f32_e32 v34, v38, v42
	v_sub_f32_e32 v48, v39, v42
	v_mul_f32_e32 v32, 0x3fb8aa3b, v32
	v_mul_f32_e32 v33, 0x3fb8aa3b, v33
	v_mul_f32_e32 v34, 0x3fb8aa3b, v34
	v_mul_f32_e32 v48, 0x3fb8aa3b, v48
	v_exp_f32_e32 v32, v32
	v_exp_f32_e32 v33, v33
	v_exp_f32_e32 v34, v34
	v_exp_f32_e32 v48, v48
	v_mul_f32_e32 v32, v8, v32
	v_mul_f32_e32 v33, v9, v33
	v_mul_f32_e32 v34, v10, v34
	v_mul_f32_e32 v48, v11, v48
	v_cndmask_b32_e64 v32, 0, v32, s[18:19]
	v_cndmask_b32_e64 v33, 0, v33, s[20:21]
	v_cndmask_b32_e64 v34, 0, v34, s[22:23]
	v_cndmask_b32_e64 v48, 0, v48, s[24:25]
	v_cvt_pk_bf16_f32 v32, v32, v32
	v_cvt_pk_bf16_f32 v33, v33, v33
	v_cvt_pk_bf16_f32 v34, v34, v34
	v_cvt_pk_bf16_f32 v48, v48, v48
	ds_write_b16 v119, v32 offset:43072
	ds_write_b16 v119, v33 offset:43344
	ds_write_b16 v119, v34 offset:43616
	ds_write_b16 v119, v48 offset:43888
	s_branch .Lml_next_2
.Lml_zero_2:
	ds_write_b16 v119, v35 offset:43072
	ds_write_b16 v119, v35 offset:43344
	ds_write_b16 v119, v35 offset:43616
	ds_write_b16 v119, v35 offset:43888
.Lml_next_2:
	s_cmp_eq_u64 s[34:35], 0
	s_cbranch_scc1 .Lml_zero_3
	v_sub_f32_e32 v32, v36, v43
	v_sub_f32_e32 v33, v37, v43
	v_sub_f32_e32 v34, v38, v43
	v_sub_f32_e32 v48, v39, v43
	v_mul_f32_e32 v32, 0x3fb8aa3b, v32
	v_mul_f32_e32 v33, 0x3fb8aa3b, v33
	v_mul_f32_e32 v34, 0x3fb8aa3b, v34
	v_mul_f32_e32 v48, 0x3fb8aa3b, v48
	v_exp_f32_e32 v32, v32
	v_exp_f32_e32 v33, v33
	v_exp_f32_e32 v34, v34
	v_exp_f32_e32 v48, v48
	v_mul_f32_e32 v32, v12, v32
	v_mul_f32_e32 v33, v13, v33
	v_mul_f32_e32 v34, v14, v34
	v_mul_f32_e32 v48, v15, v48
	v_cndmask_b32_e64 v32, 0, v32, s[26:27]
	v_cndmask_b32_e64 v33, 0, v33, s[28:29]
	v_cndmask_b32_e64 v34, 0, v34, s[30:31]
	v_cndmask_b32_e64 v48, 0, v48, s[34:35]
	v_cvt_pk_bf16_f32 v32, v32, v32
	v_cvt_pk_bf16_f32 v33, v33, v33
	v_cvt_pk_bf16_f32 v34, v34, v34
	v_cvt_pk_bf16_f32 v48, v48, v48
	ds_write_b16 v119, v32 offset:43104
	ds_write_b16 v119, v33 offset:43376
	ds_write_b16 v119, v34 offset:43648
	ds_write_b16 v119, v48 offset:43920
	s_branch .Lml_next_3
.Lml_zero_3:
	ds_write_b16 v119, v35 offset:43104
	ds_write_b16 v119, v35 offset:43376
	ds_write_b16 v119, v35 offset:43648
	ds_write_b16 v119, v35 offset:43920
.Lml_next_3:
	s_cmp_eq_u64 s[42:43], 0
	s_cbranch_scc1 .Lml_zero_4
	v_sub_f32_e32 v32, v36, v44
	v_sub_f32_e32 v33, v37, v44
	v_sub_f32_e32 v34, v38, v44
	v_sub_f32_e32 v48, v39, v44
	v_mul_f32_e32 v32, 0x3fb8aa3b, v32
	v_mul_f32_e32 v33, 0x3fb8aa3b, v33
	v_mul_f32_e32 v34, 0x3fb8aa3b, v34
	v_mul_f32_e32 v48, 0x3fb8aa3b, v48
	v_exp_f32_e32 v32, v32
	v_exp_f32_e32 v33, v33
	v_exp_f32_e32 v34, v34
	v_exp_f32_e32 v48, v48
	v_mul_f32_e32 v32, v16, v32
	v_mul_f32_e32 v33, v17, v33
	v_mul_f32_e32 v34, v18, v34
	v_mul_f32_e32 v48, v19, v48
	v_cndmask_b32_e64 v32, 0, v32, s[36:37]
	v_cndmask_b32_e64 v33, 0, v33, s[38:39]
	v_cndmask_b32_e64 v34, 0, v34, s[40:41]
	v_cndmask_b32_e64 v48, 0, v48, s[42:43]
	v_cvt_pk_bf16_f32 v32, v32, v32
	v_cvt_pk_bf16_f32 v33, v33, v33
	v_cvt_pk_bf16_f32 v34, v34, v34
	v_cvt_pk_bf16_f32 v48, v48, v48
	ds_write_b16 v119, v32 offset:43136
	ds_write_b16 v119, v33 offset:43408
	ds_write_b16 v119, v34 offset:43680
	ds_write_b16 v119, v48 offset:43952
	s_branch .Lml_next_4
.Lml_zero_4:
	ds_write_b16 v119, v35 offset:43136
	ds_write_b16 v119, v35 offset:43408
	ds_write_b16 v119, v35 offset:43680
	ds_write_b16 v119, v35 offset:43952
.Lml_next_4:
	s_cmp_eq_u64 s[50:51], 0
	s_cbranch_scc1 .Lml_zero_5
	v_sub_f32_e32 v32, v36, v45
	v_sub_f32_e32 v33, v37, v45
	v_sub_f32_e32 v34, v38, v45
	v_sub_f32_e32 v48, v39, v45
	v_mul_f32_e32 v32, 0x3fb8aa3b, v32
	v_mul_f32_e32 v33, 0x3fb8aa3b, v33
	v_mul_f32_e32 v34, 0x3fb8aa3b, v34
	v_mul_f32_e32 v48, 0x3fb8aa3b, v48
	v_exp_f32_e32 v32, v32
	v_exp_f32_e32 v33, v33
	v_exp_f32_e32 v34, v34
	v_exp_f32_e32 v48, v48
	v_mul_f32_e32 v32, v20, v32
	v_mul_f32_e32 v33, v21, v33
	v_mul_f32_e32 v34, v22, v34
	v_mul_f32_e32 v48, v23, v48
	v_cndmask_b32_e64 v32, 0, v32, s[44:45]
	v_cndmask_b32_e64 v33, 0, v33, s[46:47]
	v_cndmask_b32_e64 v34, 0, v34, s[48:49]
	v_cndmask_b32_e64 v48, 0, v48, s[50:51]
	v_cvt_pk_bf16_f32 v32, v32, v32
	v_cvt_pk_bf16_f32 v33, v33, v33
	v_cvt_pk_bf16_f32 v34, v34, v34
	v_cvt_pk_bf16_f32 v48, v48, v48
	ds_write_b16 v119, v32 offset:43168
	ds_write_b16 v119, v33 offset:43440
	ds_write_b16 v119, v34 offset:43712
	ds_write_b16 v119, v48 offset:43984
	s_branch .Lml_next_5
.Lml_zero_5:
	ds_write_b16 v119, v35 offset:43168
	ds_write_b16 v119, v35 offset:43440
	ds_write_b16 v119, v35 offset:43712
	ds_write_b16 v119, v35 offset:43984
.Lml_next_5:
	s_cmp_eq_u64 s[58:59], 0
	s_cbranch_scc1 .Lml_zero_6
	v_sub_f32_e32 v32, v36, v46
	v_sub_f32_e32 v33, v37, v46
	v_sub_f32_e32 v34, v38, v46
	v_sub_f32_e32 v48, v39, v46
	v_mul_f32_e32 v32, 0x3fb8aa3b, v32
	v_mul_f32_e32 v33, 0x3fb8aa3b, v33
	v_mul_f32_e32 v34, 0x3fb8aa3b, v34
	v_mul_f32_e32 v48, 0x3fb8aa3b, v48
	v_exp_f32_e32 v32, v32
	v_exp_f32_e32 v33, v33
	v_exp_f32_e32 v34, v34
	v_exp_f32_e32 v48, v48
	v_mul_f32_e32 v32, v24, v32
	v_mul_f32_e32 v33, v25, v33
	v_mul_f32_e32 v34, v26, v34
	v_mul_f32_e32 v48, v27, v48
	v_cndmask_b32_e64 v32, 0, v32, s[52:53]
	v_cndmask_b32_e64 v33, 0, v33, s[54:55]
	v_cndmask_b32_e64 v34, 0, v34, s[56:57]
	v_cndmask_b32_e64 v48, 0, v48, s[58:59]
	v_cvt_pk_bf16_f32 v32, v32, v32
	v_cvt_pk_bf16_f32 v33, v33, v33
	v_cvt_pk_bf16_f32 v34, v34, v34
	v_cvt_pk_bf16_f32 v48, v48, v48
	ds_write_b16 v119, v32 offset:43200
	ds_write_b16 v119, v33 offset:43472
	ds_write_b16 v119, v34 offset:43744
	ds_write_b16 v119, v48 offset:44016
	s_branch .Lml_next_6
.Lml_zero_6:
	ds_write_b16 v119, v35 offset:43200
	ds_write_b16 v119, v35 offset:43472
	ds_write_b16 v119, v35 offset:43744
	ds_write_b16 v119, v35 offset:44016
.Lml_next_6:
	s_cmp_eq_u64 s[66:67], 0
	s_cbranch_scc1 .Lml_zero_7
	v_sub_f32_e32 v32, v36, v47
	v_sub_f32_e32 v33, v37, v47
	v_sub_f32_e32 v34, v38, v47
	v_sub_f32_e32 v48, v39, v47
	v_mul_f32_e32 v32, 0x3fb8aa3b, v32
	v_mul_f32_e32 v33, 0x3fb8aa3b, v33
	v_mul_f32_e32 v34, 0x3fb8aa3b, v34
	v_mul_f32_e32 v48, 0x3fb8aa3b, v48
	v_exp_f32_e32 v32, v32
	v_exp_f32_e32 v33, v33
	v_exp_f32_e32 v34, v34
	v_exp_f32_e32 v48, v48
	v_mul_f32_e32 v32, v28, v32
	v_mul_f32_e32 v33, v29, v33
	v_mul_f32_e32 v34, v30, v34
	v_mul_f32_e32 v48, v31, v48
	v_cndmask_b32_e64 v32, 0, v32, s[60:61]
	v_cndmask_b32_e64 v33, 0, v33, s[62:63]
	v_cndmask_b32_e64 v34, 0, v34, s[64:65]
	v_cndmask_b32_e64 v48, 0, v48, s[66:67]
	v_cvt_pk_bf16_f32 v32, v32, v32
	v_cvt_pk_bf16_f32 v33, v33, v33
	v_cvt_pk_bf16_f32 v34, v34, v34
	v_cvt_pk_bf16_f32 v48, v48, v48
	ds_write_b16 v119, v32 offset:43232
	ds_write_b16 v119, v33 offset:43504
	ds_write_b16 v119, v34 offset:43776
	ds_write_b16 v119, v48 offset:44048
	s_branch .Lml_next_7
.Lml_zero_7:
	ds_write_b16 v119, v35 offset:43232
	ds_write_b16 v119, v35 offset:43504
	ds_write_b16 v119, v35 offset:43776
	ds_write_b16 v119, v35 offset:44048
.Lml_next_7:
	s_lshl_b32 s78, s96, 7
	v_lshl_add_u32 v48, s78, 2, v95
	ds_read_b32 v48, v48
	s_lshl_b32 s0, s96, 6
	s_mov_b64 s[94:95], 0
	s_waitcnt vmcnt(8)
	v_lshlrev_b32_e32 v44, 16, v132
	v_and_b32_e32 v32, 0xffff0000, v132
	s_waitcnt lgkmcnt(0)
	v_mul_f32_e32 v32, v48, v32
	s_waitcnt vmcnt(7)
	v_lshlrev_b32_e32 v41, 16, v137
	v_cvt_pk_bf16_f32 v32, v32, s0
	ds_write_b16 v102, v32 offset:2176
	v_mul_f32_e32 v32, v48, v41
	v_lshlrev_b32_e32 v45, 16, v133
	v_cvt_pk_bf16_f32 v32, v32, s0
	ds_write_b16 v100, v32 offset:544
	v_mul_f32_e32 v32, v48, v45
	v_and_b32_e32 v37, 0xffff0000, v137
	v_cvt_pk_bf16_f32 v32, v32, s0
	ds_write_b16 v103, v32 offset:2176
	v_mul_f32_e32 v32, v48, v37
	v_and_b32_e32 v33, 0xffff0000, v133
	v_cvt_pk_bf16_f32 v32, v32, s0
	ds_write_b16 v100, v32 offset:816
	v_mul_f32_e32 v32, v48, v33
	v_lshlrev_b32_e32 v42, 16, v138
	v_cvt_pk_bf16_f32 v32, v32, s0
	ds_write_b16 v104, v32 offset:2176
	v_mul_f32_e32 v32, v48, v42
	v_lshlrev_b32_e32 v46, 16, v134
	v_cvt_pk_bf16_f32 v32, v32, s0
	ds_write_b16 v100, v32 offset:1088
	v_mul_f32_e32 v32, v48, v46
	v_and_b32_e32 v38, 0xffff0000, v138
	v_cvt_pk_bf16_f32 v32, v32, s0
	ds_write_b16 v105, v32 offset:2176
	v_mul_f32_e32 v32, v48, v38
	v_and_b32_e32 v34, 0xffff0000, v134
	v_cvt_pk_bf16_f32 v32, v32, s0
	ds_write_b16 v100, v32 offset:1360
	v_mul_f32_e32 v32, v48, v34
	v_lshlrev_b32_e32 v43, 16, v139
	v_cvt_pk_bf16_f32 v32, v32, s0
	ds_write_b16 v106, v32 offset:2176
	v_mul_f32_e32 v32, v48, v43
	v_lshlrev_b32_e32 v47, 16, v135
	v_cvt_pk_bf16_f32 v32, v32, s0
	ds_write_b16 v100, v32 offset:1632
	v_mul_f32_e32 v32, v48, v47
	v_and_b32_e32 v39, 0xffff0000, v139
	v_cvt_pk_bf16_f32 v32, v32, s0
	v_lshlrev_b32_e32 v40, 16, v136
	ds_write_b16 v107, v32 offset:2176
	v_mul_f32_e32 v32, v48, v39
	v_and_b32_e32 v35, 0xffff0000, v135
	v_mul_f32_e32 v40, v48, v40
	v_cvt_pk_bf16_f32 v32, v32, s0
	v_and_b32_e32 v36, 0xffff0000, v136
	v_cvt_pk_bf16_f32 v40, v40, s0
	ds_write_b16 v100, v32 offset:1904
	v_mul_f32_e32 v32, v48, v35
	ds_write_b16 v100, v40
	v_mul_f32_e32 v40, v48, v44
	v_mul_f32_e32 v36, v48, v36
	v_cvt_pk_bf16_f32 v32, v32, s0
	v_cvt_pk_bf16_f32 v40, v40, s0
	v_cvt_pk_bf16_f32 v36, v36, s0
	ds_write_b16 v108, v32 offset:2176
	ds_write_b16 v101, v40 offset:2176
	ds_write_b16 v100, v36 offset:272
	s_waitcnt vmcnt(4)
	ds_write_b128 v114, v[140:143]
	ds_write_b128 v114, v[144:147] offset:8704
	v_mov_b32_e32 v252, v148
	v_add_lshl_u32 v253, s0, v71, 1
	v_add_co_u32_e32 v254, vcc, v76, v253
	s_nop 1
	v_addc_co_u32_e32 v255, vcc, 0, v77, vcc
	global_load_dwordx2 v[236:237], v[254:255], off
	global_load_dwordx2 v[238:239], v[254:255], off offset:32
	global_load_dwordx2 v[240:241], v[254:255], off offset:64
	global_load_dwordx2 v[242:243], v[254:255], off offset:96
	v_add_co_u32_e32 v254, vcc, v74, v253
	s_nop 1
	v_addc_co_u32_e32 v255, vcc, 0, v75, vcc
	global_load_dwordx2 v[244:245], v[254:255], off
	global_load_dwordx2 v[246:247], v[254:255], off offset:32
	global_load_dwordx2 v[248:249], v[254:255], off offset:64
	global_load_dwordx2 v[250:251], v[254:255], off offset:96
	s_waitcnt lgkmcnt(0)
	s_barrier
	s_add_i32 s98, s96, 1
	s_min_u32 s98, s98, 7
	s_lshl_b32 s100, s98, 7
	s_mov_b32 s101, 0
	v_lshl_add_u64 v[254:255], v[72:73], 0, s[100:101]
	global_load_dwordx4 v[132:135], v[254:255], off offset:16
	global_load_dwordx4 v[136:139], v[254:255], off
	s_sub_i32 s100, s98, s96
	s_lshl_b32 s100, s100, 14
	v_lshl_add_u64 v[254:255], v[80:81], 0, s[100:101]
	global_load_dwordx4 v[140:143], v[254:255], off
	s_add_i32 s100, s100, 0x2000
	v_lshl_add_u64 v[254:255], v[80:81], 0, s[100:101]
	global_load_dwordx4 v[144:147], v[254:255], off
	s_add_i32 s98, s98, s68
	s_lshl_b32 s98, s98, 2
	v_readlane_b32 s100, v235, 23
	v_readlane_b32 s101, v235, 24
	s_nop 3
	s_add_u32 s100, s100, s98
	s_addc_u32 s101, s101, 0
	global_load_dword v148, v65, s[100:101]
	v_lshl_add_u32 v64, s78, 2, v98
	ds_read_b32 v64, v64 offset:4096
	ds_read_b128 v[186:189], v91 offset:43008
	ds_read_b128 v[190:193], v96
	ds_read_b128 v[194:197], v96 offset:4352
	ds_read_b128 v[198:201], v96 offset:8704
	ds_read_b128 v[202:205], v96 offset:13056
	ds_read_b128 v[206:209], v91 offset:43072
	ds_read_b128 v[210:213], v96 offset:64
	ds_read_b128 v[214:217], v96 offset:4416
	ds_read_b128 v[218:221], v96 offset:8768
	ds_read_b128 v[222:225], v96 offset:13120
	s_add_i32 s94, s96, s68
	s_mov_b32 s95, s79
	s_lshl_b64 vcc, s[94:95], 2
	v_readlane_b32 s80, v235, 23
	v_readlane_b32 s94, v235, 37
	v_readlane_b32 s81, v235, 24
	v_readlane_b32 s95, v235, 38
	s_add_u32 s94, s80, vcc_lo
	s_addc_u32 s95, s81, vcc_hi
	s_add_i32 s96, s96, 1
	s_cmp_eq_u32 s96, 8
	v_readlane_b32 s82, v235, 25
	v_readlane_b32 s83, v235, 26
	v_readlane_b32 s84, v235, 27
	v_readlane_b32 s85, v235, 28
	v_readlane_b32 s86, v235, 29
	v_readlane_b32 s87, v235, 30
	v_readlane_b32 s88, v235, 31
	v_readlane_b32 s89, v235, 32
	v_readlane_b32 s90, v235, 33
	v_readlane_b32 s91, v235, 34
	v_readlane_b32 s92, v235, 35
	v_readlane_b32 s93, v235, 36
	s_waitcnt lgkmcnt(5)
	v_mfma_f32_16x16x32_bf16 v[56:59], v[190:193], v[186:189], 0
	v_mfma_f32_16x16x32_bf16 v[48:51], v[194:197], v[186:189], 0
	v_mfma_f32_16x16x32_bf16 v[40:43], v[198:201], v[186:189], 0
	v_mfma_f32_16x16x32_bf16 v[32:35], v[202:205], v[186:189], 0
	ds_read_b128 v[186:189], v91 offset:43136
	ds_read_b128 v[190:193], v96 offset:128
	ds_read_b128 v[194:197], v96 offset:4480
	ds_read_b128 v[198:201], v96 offset:8832
	ds_read_b128 v[202:205], v96 offset:13184
	v_mul_f32_e32 v64, 0x3fb8aa3b, v64
	v_exp_f32_e32 v82, v64
	v_add_lshl_u32 v64, s0, v71, 1
	s_waitcnt lgkmcnt(5)
	v_mfma_f32_16x16x32_bf16 v[56:59], v[210:213], v[206:209], v[56:59]
	v_mfma_f32_16x16x32_bf16 v[48:51], v[214:217], v[206:209], v[48:51]
	v_mfma_f32_16x16x32_bf16 v[40:43], v[218:221], v[206:209], v[40:43]
	v_mfma_f32_16x16x32_bf16 v[32:35], v[222:225], v[206:209], v[32:35]
	ds_read_b128 v[206:209], v91 offset:43200
	ds_read_b128 v[210:213], v96 offset:192
	ds_read_b128 v[214:217], v96 offset:4544
	ds_read_b128 v[218:221], v96 offset:8896
	ds_read_b128 v[222:225], v96 offset:13248
	s_waitcnt lgkmcnt(5)
	v_mfma_f32_16x16x32_bf16 v[56:59], v[190:193], v[186:189], v[56:59]
	v_mfma_f32_16x16x32_bf16 v[48:51], v[194:197], v[186:189], v[48:51]
	v_mfma_f32_16x16x32_bf16 v[40:43], v[198:201], v[186:189], v[40:43]
	v_mfma_f32_16x16x32_bf16 v[32:35], v[202:205], v[186:189], v[32:35]
	ds_read_b128 v[186:189], v91 offset:8192
	ds_read_b128 v[190:193], v97
	ds_read_b128 v[194:197], v97 offset:4352
	ds_read_b128 v[198:201], v97 offset:8704
	ds_read_b128 v[202:205], v97 offset:13056
	s_waitcnt lgkmcnt(5)
	v_mfma_f32_16x16x32_bf16 v[56:59], v[210:213], v[206:209], v[56:59]
	v_mfma_f32_16x16x32_bf16 v[48:51], v[214:217], v[206:209], v[48:51]
	v_mfma_f32_16x16x32_bf16 v[40:43], v[218:221], v[206:209], v[40:43]
	v_mfma_f32_16x16x32_bf16 v[32:35], v[222:225], v[206:209], v[32:35]
	ds_read_b128 v[206:209], v91 offset:8256
	ds_read_b128 v[210:213], v97 offset:64
	ds_read_b128 v[214:217], v97 offset:4416
	ds_read_b128 v[218:221], v97 offset:8768
	ds_read_b128 v[222:225], v97 offset:13120
	s_waitcnt lgkmcnt(5)
	v_mfma_f32_16x16x32_bf16 v[60:63], v[190:193], v[186:189], 0
	v_mfma_f32_16x16x32_bf16 v[52:55], v[194:197], v[186:189], 0
	v_mfma_f32_16x16x32_bf16 v[44:47], v[198:201], v[186:189], 0
	v_mfma_f32_16x16x32_bf16 v[36:39], v[202:205], v[186:189], 0
	ds_read_b128 v[186:189], v91 offset:8320
	ds_read_b128 v[190:193], v97 offset:128
	ds_read_b128 v[194:197], v97 offset:4480
	ds_read_b128 v[198:201], v97 offset:8832
	ds_read_b128 v[202:205], v97 offset:13184
	s_waitcnt lgkmcnt(5)
	v_mfma_f32_16x16x32_bf16 v[60:63], v[210:213], v[206:209], v[60:63]
	v_mfma_f32_16x16x32_bf16 v[52:55], v[214:217], v[206:209], v[52:55]
	v_mfma_f32_16x16x32_bf16 v[44:47], v[218:221], v[206:209], v[44:47]
	v_mfma_f32_16x16x32_bf16 v[36:39], v[222:225], v[206:209], v[36:39]
	ds_read_b128 v[206:209], v91 offset:8384
	ds_read_b128 v[210:213], v97 offset:192
	ds_read_b128 v[214:217], v97 offset:4544
	ds_read_b128 v[218:221], v97 offset:8896
	ds_read_b128 v[222:225], v97 offset:13248
	s_waitcnt lgkmcnt(5)
	v_mfma_f32_16x16x32_bf16 v[60:63], v[190:193], v[186:189], v[60:63]
	v_mfma_f32_16x16x32_bf16 v[52:55], v[194:197], v[186:189], v[52:55]
	v_mfma_f32_16x16x32_bf16 v[44:47], v[198:201], v[186:189], v[44:47]
	v_mfma_f32_16x16x32_bf16 v[36:39], v[202:205], v[186:189], v[36:39]
	s_waitcnt lgkmcnt(0)
	v_mfma_f32_16x16x32_bf16 v[60:63], v[210:213], v[206:209], v[60:63]
	v_mfma_f32_16x16x32_bf16 v[52:55], v[214:217], v[206:209], v[52:55]
	v_mfma_f32_16x16x32_bf16 v[44:47], v[218:221], v[206:209], v[44:47]
	v_mfma_f32_16x16x32_bf16 v[36:39], v[222:225], v[206:209], v[36:39]
	s_nop 7
	s_nop 1
	v_pk_fma_f32 v[56:57], v[60:61], v[82:83], v[56:57] op_sel_hi:[1,0,1]
	v_pk_fma_f32 v[58:59], v[62:63], v[82:83], v[58:59] op_sel_hi:[1,0,1]
	v_pk_fma_f32 v[48:49], v[52:53], v[82:83], v[48:49] op_sel_hi:[1,0,1]
	v_pk_fma_f32 v[50:51], v[54:55], v[82:83], v[50:51] op_sel_hi:[1,0,1]
	v_pk_fma_f32 v[40:41], v[44:45], v[82:83], v[40:41] op_sel_hi:[1,0,1]
	v_pk_fma_f32 v[42:43], v[46:47], v[82:83], v[42:43] op_sel_hi:[1,0,1]
	v_pk_fma_f32 v[32:33], v[36:37], v[82:83], v[32:33] op_sel_hi:[1,0,1]
	v_pk_fma_f32 v[34:35], v[38:39], v[82:83], v[34:35] op_sel_hi:[1,0,1]
	s_mov_b64 s[0:1], 0x4000
	v_lshl_add_u64 v[80:81], v[80:81], 0, s[0:1]
	s_waitcnt vmcnt(12)
	v_lshlrev_b32_e32 v128, 16, v236
	v_and_b32_e32 v129, 0xffff0000, v236
	s_waitcnt vmcnt(8)
	v_lshlrev_b32_e32 v126, 16, v244
	v_and_b32_e32 v127, 0xffff0000, v244
	v_mul_f32_e32 v122, 0xbfb8aa3b, v128
	v_mul_f32_e32 v60, 0xbfb8aa3b, v129
	v_exp_f32_e32 v122, v122
	v_exp_f32_e32 v60, v60
	v_pk_fma_f32 v[56:57], v[252:253], v[126:127], v[56:57] op_sel_hi:[0,1,1]
	v_add_f32_e32 v122, 1.0, v122
	v_add_f32_e32 v60, 1.0, v60
	v_rcp_f32_e32 v130, v122
	v_rcp_f32_e32 v131, v60
	v_lshlrev_b32_e32 v122, 16, v237
	v_pk_mul_f32 v[60:61], v[130:131], v[128:129]
	s_nop 0
	v_pk_mul_f32 v[56:57], v[56:57], v[60:61]
	s_nop 0
	v_pk_mul_f32 v[60:61], v[56:57], v[56:57]
	s_nop 0
	v_add_f32_e32 v60, v121, v60
	v_add_f32_e32 v61, v61, v60
	v_cvt_pk_bf16_f32 v60, v56, v57
	v_lshlrev_b32_e32 v56, 16, v245
	v_and_b32_e32 v57, 0xffff0000, v245
	v_and_b32_e32 v123, 0xffff0000, v237
	v_mul_f32_e32 v121, 0xbfb8aa3b, v122
	v_pk_fma_f32 v[56:57], v[252:253], v[56:57], v[58:59] op_sel_hi:[0,1,1]
	v_mul_f32_e32 v58, 0xbfb8aa3b, v123
	v_exp_f32_e32 v121, v121
	v_exp_f32_e32 v58, v58
	v_add_f32_e32 v121, 1.0, v121
	v_add_f32_e32 v58, 1.0, v58
	v_rcp_f32_e32 v124, v121
	v_rcp_f32_e32 v125, v58
	s_nop 0
	v_pk_mul_f32 v[58:59], v[124:125], v[122:123]
	s_nop 0
	v_pk_mul_f32 v[56:57], v[56:57], v[58:59]
	s_nop 0
	v_pk_mul_f32 v[58:59], v[56:57], v[56:57]
	s_nop 0
	v_add_f32_e32 v58, v58, v61
	v_cvt_pk_bf16_f32 v61, v56, v57
	v_lshl_add_u64 v[56:57], v[78:79], 0, v[64:65]
	global_store_dwordx2 v[56:57], v[60:61], off
	v_add_f32_e32 v121, v59, v58
	s_waitcnt vmcnt(8)
	v_lshlrev_b32_e32 v62, 16, v246
	s_waitcnt vmcnt(12)
	v_lshlrev_b32_e32 v122, 16, v238
	v_and_b32_e32 v123, 0xffff0000, v238
	v_and_b32_e32 v63, 0xffff0000, v246
	v_mul_f32_e32 v58, 0xbfb8aa3b, v122
	v_mul_f32_e32 v52, 0xbfb8aa3b, v123
	v_exp_f32_e32 v58, v58
	v_exp_f32_e32 v52, v52
	v_pk_fma_f32 v[48:49], v[252:253], v[62:63], v[48:49] op_sel_hi:[0,1,1]
	v_add_f32_e32 v58, 1.0, v58
	v_add_f32_e32 v52, 1.0, v52
	v_rcp_f32_e32 v124, v58
	v_rcp_f32_e32 v125, v52
	v_lshlrev_b32_e32 v58, 16, v239
	v_pk_mul_f32 v[52:53], v[124:125], v[122:123]
	s_nop 0
	v_pk_mul_f32 v[48:49], v[48:49], v[52:53]
	s_nop 0
	v_pk_mul_f32 v[52:53], v[48:49], v[48:49]
	v_cvt_pk_bf16_f32 v48, v48, v49
	v_mul_f32_e32 v49, 0xbfb8aa3b, v58
	v_exp_f32_e32 v49, v49
	v_add_f32_e32 v52, v52, v121
	v_add_f32_e32 v62, v53, v52
	v_lshlrev_b32_e32 v52, 16, v247
	v_and_b32_e32 v53, 0xffff0000, v247
	v_and_b32_e32 v59, 0xffff0000, v239
	v_add_f32_e32 v49, 1.0, v49
	v_rcp_f32_e32 v60, v49
	v_mul_f32_e32 v49, 0xbfb8aa3b, v59
	v_exp_f32_e32 v49, v49
	v_pk_fma_f32 v[50:51], v[252:253], v[52:53], v[50:51] op_sel_hi:[0,1,1]
	v_add_f32_e32 v49, 1.0, v49
	v_rcp_f32_e32 v61, v49
	s_nop 0
	v_pk_mul_f32 v[52:53], v[60:61], v[58:59]
	s_nop 0
	v_pk_mul_f32 v[50:51], v[50:51], v[52:53]
	s_nop 0
	v_pk_mul_f32 v[52:53], v[50:51], v[50:51]
	s_nop 0
	v_add_f32_e32 v49, v52, v62
	v_add_f32_e32 v60, v53, v49
	v_cvt_pk_bf16_f32 v49, v50, v51
	global_store_dwordx2 v[56:57], v[48:49], off offset:32
	s_waitcnt vmcnt(8)
	v_lshlrev_b32_e32 v52, 16, v248
	s_waitcnt vmcnt(12)
	v_lshlrev_b32_e32 v54, 16, v240
	v_and_b32_e32 v55, 0xffff0000, v240
	v_and_b32_e32 v53, 0xffff0000, v248
	v_mul_f32_e32 v48, 0xbfb8aa3b, v54
	v_mul_f32_e32 v44, 0xbfb8aa3b, v55
	v_exp_f32_e32 v48, v48
	v_exp_f32_e32 v44, v44
	v_pk_fma_f32 v[40:41], v[252:253], v[52:53], v[40:41] op_sel_hi:[0,1,1]
	v_add_f32_e32 v48, 1.0, v48
	v_add_f32_e32 v44, 1.0, v44
	v_rcp_f32_e32 v58, v48
	v_rcp_f32_e32 v59, v44
	v_lshlrev_b32_e32 v48, 16, v241
	v_pk_mul_f32 v[44:45], v[58:59], v[54:55]
	s_nop 0
	v_pk_mul_f32 v[40:41], v[40:41], v[44:45]
	s_nop 0
	v_pk_mul_f32 v[44:45], v[40:41], v[40:41]
	v_cvt_pk_bf16_f32 v40, v40, v41
	v_mul_f32_e32 v41, 0xbfb8aa3b, v48
	v_exp_f32_e32 v41, v41
	v_add_f32_e32 v44, v44, v60
	v_add_f32_e32 v52, v45, v44
	v_lshlrev_b32_e32 v44, 16, v249
	v_and_b32_e32 v45, 0xffff0000, v249
	v_and_b32_e32 v49, 0xffff0000, v241
	v_add_f32_e32 v41, 1.0, v41
	v_rcp_f32_e32 v50, v41
	v_mul_f32_e32 v41, 0xbfb8aa3b, v49
	v_exp_f32_e32 v41, v41
	v_pk_fma_f32 v[42:43], v[252:253], v[44:45], v[42:43] op_sel_hi:[0,1,1]
	v_add_f32_e32 v41, 1.0, v41
	v_rcp_f32_e32 v51, v41
	s_nop 0
	v_pk_mul_f32 v[44:45], v[50:51], v[48:49]
	s_nop 0
	v_pk_mul_f32 v[42:43], v[42:43], v[44:45]
	s_nop 0
	v_pk_mul_f32 v[44:45], v[42:43], v[42:43]
	s_nop 0
	v_add_f32_e32 v41, v44, v52
	v_add_f32_e32 v50, v45, v41
	v_cvt_pk_bf16_f32 v41, v42, v43
	global_store_dwordx2 v[56:57], v[40:41], off offset:64
	s_waitcnt vmcnt(8)
	v_lshlrev_b32_e32 v44, 16, v250
	s_waitcnt vmcnt(12)
	v_lshlrev_b32_e32 v46, 16, v242
	v_and_b32_e32 v47, 0xffff0000, v242
	v_and_b32_e32 v45, 0xffff0000, v250
	v_mul_f32_e32 v40, 0xbfb8aa3b, v46
	v_mul_f32_e32 v36, 0xbfb8aa3b, v47
	v_exp_f32_e32 v40, v40
	v_exp_f32_e32 v36, v36
	v_pk_fma_f32 v[32:33], v[252:253], v[44:45], v[32:33] op_sel_hi:[0,1,1]
	v_add_f32_e32 v40, 1.0, v40
	v_add_f32_e32 v36, 1.0, v36
	v_rcp_f32_e32 v48, v40
	v_rcp_f32_e32 v49, v36
	v_lshlrev_b32_e32 v40, 16, v243
	v_pk_mul_f32 v[36:37], v[48:49], v[46:47]
	s_nop 0
	v_pk_mul_f32 v[32:33], v[32:33], v[36:37]
	s_nop 0
	v_pk_mul_f32 v[36:37], v[32:33], v[32:33]
	v_cvt_pk_bf16_f32 v32, v32, v33
	v_mul_f32_e32 v33, 0xbfb8aa3b, v40
	v_exp_f32_e32 v33, v33
	v_add_f32_e32 v36, v36, v50
	v_add_f32_e32 v44, v37, v36
	v_lshlrev_b32_e32 v36, 16, v251
	v_and_b32_e32 v37, 0xffff0000, v251
	v_and_b32_e32 v41, 0xffff0000, v243
	v_add_f32_e32 v33, 1.0, v33
	v_rcp_f32_e32 v42, v33
	v_mul_f32_e32 v33, 0xbfb8aa3b, v41
	v_exp_f32_e32 v33, v33
	v_pk_fma_f32 v[34:35], v[252:253], v[36:37], v[34:35] op_sel_hi:[0,1,1]
	v_add_f32_e32 v33, 1.0, v33
	v_rcp_f32_e32 v43, v33
	s_nop 0
	v_pk_mul_f32 v[36:37], v[42:43], v[40:41]
	s_nop 0
	v_pk_mul_f32 v[34:35], v[34:35], v[36:37]
	s_nop 0
	v_pk_mul_f32 v[36:37], v[34:35], v[34:35]
	s_nop 0
	v_add_f32_e32 v33, v36, v44
	v_add_f32_e32 v121, v37, v33
	v_cvt_pk_bf16_f32 v33, v34, v35
	global_store_dwordx2 v[56:57], v[32:33], off offset:96
	s_barrier
	s_cbranch_scc0 .LBB0_651
	ds_bpermute_b32 v0, v109, v121
	v_lshl_or_b32 v4, v120, 9, v93
	v_readlane_b32 s0, v234, 23
	v_lshlrev_b32_e32 v64, 2, v4
	v_readlane_b32 s1, v234, 24
	s_waitcnt lgkmcnt(0)
	v_add_f32_e32 v5, v121, v0
	ds_bpermute_b32 v6, v110, v5
	v_lshl_add_u64 v[0:1], s[0:1], 0, v[64:65]
	s_mov_b32 s0, 0x800000
	v_add_u32_e32 v2, s73, v92
	v_ashrrev_i32_e32 v3, 31, v2
	s_waitcnt lgkmcnt(0)
	v_add_f32_e32 v5, v5, v6
	v_fmamk_f32 v5, v5, 0x3b000000, v118
	v_mul_f32_e32 v6, 0x4b800000, v5
	v_cmp_gt_f32_e32 vcc, s0, v5
	v_lshlrev_b64 v[2:3], 12, v[2:3]
	v_lshl_or_b32 v2, v4, 1, v2
	v_cndmask_b32_e32 v5, v5, v6, vcc
	v_rsq_f32_e32 v5, v5
	v_readlane_b32 s84, v234, 11
	v_readlane_b32 s86, v234, 13
	v_readlane_b32 s87, v234, 14
	v_mul_f32_e32 v4, 0x45800000, v5
	v_cndmask_b32_e32 v4, v5, v4, vcc
	v_lshl_add_u64 v[2:3], s[86:87], 0, v[2:3]
	v_mov_b32_e32 v5, v4
	s_mov_b64 s[94:95], 0
	v_readlane_b32 s85, v234, 12
